# v24: v23 + 64-byte alignment of attention, SGU and row-phase loop heads
# baseline (speedup 1.0000x reference)
; __device__ __forceinline__ float wave_sum(float v) {
; #pragma unroll
;     for (int o = 1; o < 64; o <<= 1) v += __shfl_xor(v, o);
;     return v;
; }
; __global__ void __launch_bounds__(512, 2) fwd_megakernel(Args a) {
;     ...
;     for (int row = gw * (ML / NGW), rend = row + ML / NGW; row < rend; row += 4) {
;         const float* md = MOD + (size_t)(row >> 13) * 6144;
;         row_op<4>(a.in[0] + (size_t)row * DM, nullptr, nullptr, nullptr, nullptr, HX + (size_t)row * DM, a.in[6], md + 1024, md, lane);
;     }
.LBB0_82:
	s_or_b64 exec, exec, s[0:1]
	s_abs_i32 s0, s96
	v_cvt_f32_u32_e32 v0, s0
	s_sub_i32 s1, 0, s0
	s_lshr_b32 s54, s33, 6
	s_ashr_i32 s97, s96, 31
	v_rcp_iflag_f32_e32 v0, v0
	s_add_i32 s7, s54, s18
	v_writelane_b32 v252, s7, 14
	v_and_b32_e32 v228, 63, v179
	v_mul_f32_e32 v0, 0x4f7ffffe, v0
	v_cvt_u32_f32_e32 v0, v0
	v_mbcnt_lo_u32_b32 v77, -1, 0
	s_barrier
	v_readfirstlane_b32 s4, v0
	s_mul_i32 s1, s1, s4
	s_mul_hi_u32 s1, s4, s1
	s_add_i32 s4, s4, s1
	s_lshr_b32 s1, s4, 16
	s_mul_i32 s4, s1, s0
	s_sub_i32 s4, 0x10000, s4
	s_add_i32 s5, s1, 1
	s_sub_i32 s6, s4, s0
	s_cmp_ge_u32 s4, s0
	s_cselect_b32 s1, s5, s1
	s_cselect_b32 s4, s6, s4
	s_add_i32 s5, s1, 1
	s_cmp_ge_u32 s4, s0
	s_cselect_b32 s0, s5, s1
	s_xor_b32 s0, s0, s97
	s_sub_i32 s0, s0, s97
	s_mul_i32 s4, s0, s7
	s_add_i32 s58, s4, s0
	s_cmp_gt_i32 s0, 0
	s_mov_b32 s56, s4
	s_cselect_b64 s[4:5], -1, 0
	v_writelane_b32 v252, s4, 15
	s_cmp_lt_i32 s0, 1
	s_nop 0
	v_writelane_b32 v252, s5, 16
	s_nop 0
	v_readlane_b32 s24, v252, 8
	v_readlane_b32 s25, v252, 9
	s_cbranch_scc1 .LBB0_85
	s_mov_b32 s6, s56
	s_ashr_i32 s7, s56, 31
	s_lshl_b64 s[0:1], s[6:7], 12
	s_add_u32 s0, s16, s0
	s_addc_u32 s1, s17, s1
	s_lshl_b64 s[4:5], s[6:7], 11
	s_add_u32 s4, s60, s4
	s_addc_u32 s5, s61, s5
	v_mbcnt_hi_u32_b32 v79, -1, v77
	s_add_u32 s10, s4, 0x3000000
	v_and_b32_e32 v0, 64, v79
	s_mov_b32 s4, 0x358637bd
	s_addc_u32 s11, s5, 0
	s_movk_i32 s13, 0x1000
	s_movk_i32 s18, 0x2000
	s_movk_i32 s19, 0x3000
	v_add_u32_e32 v81, 64, v0
	v_xor_b32_e32 v83, 1, v79
	v_xor_b32_e32 v84, 2, v79
	v_xor_b32_e32 v85, 4, v79
	v_xor_b32_e32 v86, 8, v79
	v_xor_b32_e32 v87, 16, v79
	v_xor_b32_e32 v88, 32, v79
	s_mov_b32 s12, 0x3a800000
	v_mov_b64_e32 v[64:65], s[4:5]
	s_mov_b32 s22, 0x800000
	s_mov_b64 s[14:15], 0x1000
	s_mov_b32 s23, s56
	.p2align	6

; __device__ __forceinline__ void attn_units(LAS unsigned char* lds, const bf16* QB, const bf16* KB, const bf16* VT, const bf16* VTc, bf16* MIX, const float* sink, const float* gmix,
;                                            int nunits, int G, int vb, int tid) {
;     ...
;         for (;;) {
;             int sn = s + 1; if (sn == 2 && !isctx && nb == 63) sn = 3;
;             if (sn <= 4) AT_ISSUE(sn);
.LBB0_303:
	s_mov_b32 s67, s63
	s_andn2_b64 vcc, exec, s[34:35]
	s_cbranch_vccz .LBB0_334
	.p2align	6

; __device__ __forceinline__ unsigned cvt_pk_bf16(float lo, float hi) { unsigned r; asm volatile("v_cvt_pk_bf16_f32 %0, %1, %2" : "=v"(r) : "v"(lo), "v"(hi)); return r; }
; #define LAS __attribute__((address_space(3)))
; #define MFMA32(a, b, c) __builtin_amdgcn_mfma_f32_32x32x16_bf16(a, b, c, 0, 0, 0)
; __device__ __forceinline__ void attn_units(LAS unsigned char* lds, const bf16* QB, const bf16* KB, const bf16* VT, const bf16* VTc, bf16* MIX, const float* sink, const float* gmix,
;                                            int nunits, int G, int vb, int tid) {
;     ...
;             const LAS bf16* Ks = (const LAS bf16*)(lds + cur * AT_BUF); const LAS bf16* Vs = (const LAS bf16*)(lds + cur * AT_BUF + AT_HALF);
;             int t_lo = 0, t_hi = 3; const int kb0 = (nb - 1 + s) * 128;
;             if (s < 3) { const int a0 = q0 - 128 - kb0, a1 = q0 + 191 - kb0; t_lo = a0 > 0 ? a0 >> 5 : 0; t_hi = (a1 >> 5) < 3 ? (a1 >> 5) : 3; }
; #pragma unroll 2
;             for (int kt = t_lo; kt <= t_hi; ++kt) {
;     ...
;                     float psum = 0.f;
; #pragma unroll
;                     for (int r = 0; r < 16; ++r) { t[r] = __builtin_amdgcn_exp2f(t[r]); psum += t[r]; }
;                     { auto rr = __builtin_amdgcn_permlane32_swap(__float_as_uint(psum), __float_as_uint(psum), false, false); psum = __uint_as_float(rr[0]) + __uint_as_float(rr[1]); }
;                     lrun[qs] += psum;
; #pragma unroll
;                     for (int s2 = 0; s2 < 2; ++s2) { v4u w; w.x = cvt_pk_bf16(t[8 * s2 + 0], t[8 * s2 + 1]); w.y = cvt_pk_bf16(t[8 * s2 + 2], t[8 * s2 + 3]); w.z = cvt_pk_bf16(t[8 * s2 + 4], t[8 * s2 + 5]); w.w = cvt_pk_bf16(t[8 * s2 + 6], t[8 * s2 + 7]);
;                         pb[qs][s2] = __builtin_bit_cast(bf16x8, w); }
; #pragma unroll
;                     for (int s2 = 0; s2 < 2; ++s2)
; #pragma unroll
;                         for (int dt = 0; dt < 2; ++dt) o[qs][dt] = MFMA32(vf[dt][s2], pb[qs][s2], o[qs][dt]);
.LBB0_311:
	s_add_i32 s4, s63, s43
	s_lshl_b32 s4, s4, 7
	s_sub_i32 s5, s23, s4
	s_sub_i32 s4, s64, s4
	s_max_i32 s5, s5, 0
	s_ashr_i32 s4, s4, 5
	s_lshr_b32 s8, s5, 5
	s_min_i32 s9, s4, 3
	s_cmp_lt_i32 s63, 3
	s_cselect_b64 s[40:41], -1, 0
	s_and_b64 s[4:5], s[40:41], exec
	s_cselect_b32 s4, s8, 0
	s_cselect_b32 s18, s9, 3
	s_cmp_gt_i32 s4, s18
	s_cbranch_scc1 .LBB0_332
	s_mul_i32 s5, s22, 0x11400
	s_lshl_b32 s8, s4, 6
	s_add_i32 s8, s5, s8
	v_add_u32_e32 v251, s8, v241
	s_mul_i32 s8, s4, 0x2200
	s_add_i32 s19, s4, -1
	s_add_i32 s5, s5, s8
	s_lshl_b32 s4, s4, 5
	s_add_i32 s8, s30, s63
	v_add_u32_e32 v229, s5, v242
	s_sub_i32 s5, s65, s4
	s_lshl_b32 s8, s8, 7
	s_sub_i32 s46, s5, s8
	s_add_i32 s5, s66, s8
	s_add_i32 s68, s5, s4
	s_branch .LBB0_315
	.p2align	6
.LBB0_313:
	v_exp_f32_e32 v64, v64
	v_exp_f32_e32 v65, v65
	v_exp_f32_e32 v66, v66
	v_exp_f32_e32 v67, v67
	v_add_f32_e32 v80, 0, v64
	v_exp_f32_e32 v68, v68
	v_add_f32_e32 v80, v80, v65
	v_exp_f32_e32 v69, v69
	v_add_f32_e32 v80, v66, v80
	v_exp_f32_e32 v70, v70
	v_add_f32_e32 v80, v67, v80
	v_exp_f32_e32 v71, v71
	v_add_f32_e32 v80, v68, v80
	v_exp_f32_e32 v72, v72
	v_cvt_pk_bf16_f32 v64, v64, v65
	v_cvt_pk_bf16_f32 v65, v66, v67
	v_cvt_pk_bf16_f32 v66, v68, v69
	v_cvt_pk_bf16_f32 v67, v70, v71
	v_add_f32_e32 v80, v69, v80
	s_waitcnt lgkmcnt(3)
	v_mfma_f32_32x32x16_bf16 v[16:31], v[172:175], v[64:67], v[16:31]
	v_exp_f32_e32 v73, v73
	v_add_f32_e32 v80, v70, v80
	v_exp_f32_e32 v74, v74
	v_add_f32_e32 v80, v71, v80
	v_exp_f32_e32 v75, v75
	v_add_f32_e32 v80, v72, v80
	v_exp_f32_e32 v76, v76
	s_waitcnt lgkmcnt(1)
	v_mfma_f32_32x32x16_bf16 v[0:15], v[168:171], v[64:67], v[0:15]
	v_add_f32_e32 v80, v73, v80
	v_exp_f32_e32 v77, v77
	v_add_f32_e32 v80, v74, v80
	v_exp_f32_e32 v78, v78
	v_add_f32_e32 v80, v75, v80
	v_exp_f32_e32 v79, v79
	v_add_f32_e32 v80, v76, v80
	v_cvt_pk_bf16_f32 v68, v72, v73
	v_cvt_pk_bf16_f32 v69, v74, v75
	v_cvt_pk_bf16_f32 v70, v76, v77
	v_cvt_pk_bf16_f32 v71, v78, v79
	v_add_f32_e32 v80, v77, v80
	v_mfma_f32_32x32x16_bf16 v[16:31], v[164:167], v[68:71], v[16:31]
	v_add_f32_e32 v80, v78, v80
	v_add_f32_e32 v80, v79, v80
	v_mov_b32_e32 v81, v80
	s_nop 1
	v_permlane32_swap_b32_e32 v80, v81
	v_add_f32_e32 v80, v80, v81
	v_add_f32_e32 v247, v247, v80
	s_waitcnt lgkmcnt(0)
	v_mfma_f32_32x32x16_bf16 v[0:15], v[160:163], v[68:71], v[0:15]
	.p2align	6

; __device__ __forceinline__ void sgu_units(LAS unsigned char* lds, const bf16* UB, const bf16* GVT, const bf16* GVTc, bf16* MIX, const float* wsgu, const float* bsgu, const float* gsgu, const float* gmix,
;                                           int nchunks, int G, int bid, int tid) {
;     ...
;         const int chunk = (L < 512 && (G & 7) == 0) ? (L & 7) * 64 + (L >> 3) : L;
;         const bool isctx = chunk >= 512; const int b = isctx ? (chunk - 512) >> 1 : chunk >> 6, s0 = isctx ? ((chunk - 512) & 1) * 128 : (chunk & 63) * 128;
;         const int ld = isctx ? CTXL : SEQ;
;         const bf16* Gt = (isctx ? GVTc + ((size_t)(b * 256 + hd * 64)) * CTXL : GVT + ((size_t)(b * 256 + hd * 64)) * SEQ) + s0;
;         float sa = 0.f, sb = 0.f;
; #pragma unroll 1
;         for (int d0 = 0; d0 < 64; d0 += 32) { unsigned gv[32];
.LBB0_347:
	s_and_b64 s[26:27], s[14:15], exec
	s_movk_i32 s7, 0x1f80
	s_cselect_b32 s7, 0x80, s7
	s_and_b32 s7, s7, s9
	s_add_u32 s13, s60, s22
	s_addc_u32 s19, s61, s23
	s_ashr_i32 s9, s8, 31
	s_lshl_b64 s[8:9], s[8:9], s18
	s_add_u32 s8, s13, s8
	s_addc_u32 s9, s19, s9
	s_lshl_b32 s7, s7, 1
	s_add_u32 s26, s8, s7
	s_addc_u32 s27, s9, 0
	v_mov_b32_e32 v2, 0
	v_lshl_add_u64 v[0:1], s[26:27], 0, v[176:177]
	s_mov_b32 s46, 0
	s_mov_b64 s[34:35], -1
	v_mov_b32_e32 v3, v2
	.p2align	6

; __global__ void __launch_bounds__(512, 2) fwd_megakernel(Args a) {
;     ...
;         for (int row = gw * (ML / NGW), rend = row + ML / NGW; row < rend; row += 4) {
;             const float* md = modl + (size_t)(row >> 13) * 6144;
;             const float* xin = l == 0 ? a.in[0] + (size_t)row * DM : a.out + (size_t)row * DM;
;             row_op<4>(xin, YB + (size_t)row * DM, md + 2048, a.in[14] + l * 1024, nullptr, HX + (size_t)row * DM, a.in[15] + l * 1024, md + 4096, md + 3072, lane);
;         }
.LBB0_651:
	s_or_b64 exec, exec, s[0:1]
	s_mul_i32 s0, s40, 0x36000
	v_readlane_b32 s4, v252, 8
	s_add_u32 s42, s4, s0
	v_readlane_b32 s0, v252, 15
	v_readlane_b32 s1, v252, 16
	v_readlane_b32 s5, v252, 9
	s_addc_u32 s43, s5, 0
	s_waitcnt lgkmcnt(0)
	v_cndmask_b32_e64 v0, 0, 1, s[0:1]
	v_cmp_ne_u32_e64 s[10:11], 1, v0
	s_andn2_b64 vcc, exec, s[0:1]
	s_mov_b64 s[18:19], 0x2000
	s_barrier
	s_cbranch_vccnz .LBB0_654
	v_readlane_b32 s4, v255, 1
	v_readlane_b32 s5, v255, 2
	s_add_u32 s0, s92, s4
	s_addc_u32 s1, s93, s5
	s_add_u32 s26, s94, s4
	s_addc_u32 s27, s95, s5
	s_add_u32 s34, s16, s78
	v_readlane_b32 s36, v254, 14
	s_addc_u32 s35, s17, s79
	v_readlane_b32 s37, v254, 15
	v_readlane_b32 s4, v254, 22
	v_readlane_b32 s5, v254, 23
	.p2align	6

; __global__ void __launch_bounds__(512, 2) fwd_megakernel(Args a) {
;     ...
;         if (!last) for (int row = ML + gw; row < MT; row += NGW) {
;             const float* md = modl + (size_t)8 * 6144;
;             row_op<1, 4>(a.in[2] + (size_t)(row - ML) * DM, (const bf16*)((const float*)(ws + WS_PART) + (size_t)(row - ML) * DM), md + 2048, a.in[14] + l * 1024, X1C + (size_t)row * DM, HX + (size_t)row * DM, a.in[15] + l * 1024, md + 4096, md + 3072, lane);
;         }
.LBB0_654:
	v_readlane_b32 s0, v253, 30
	v_readlane_b32 s4, v254, 20
	v_readlane_b32 s1, v253, 31
	v_readlane_b32 s5, v254, 21
	s_or_b64 s[0:1], s[4:5], s[0:1]
	s_and_b64 vcc, exec, s[0:1]
	s_mov_b32 s22, 0x1800000
	s_mov_b32 s23, 0x3800000
	s_mov_b32 s24, 0x3000000
	s_cbranch_vccnz .LBB0_657
	s_add_u32 s0, s42, 0x32000
	s_addc_u32 s1, s43, 0
	v_readlane_b32 s4, v255, 1
	v_readlane_b32 s5, v255, 2
	s_add_u32 s12, s92, s4
	s_addc_u32 s13, s93, s5
	s_add_u32 s26, s94, s4
	s_addc_u32 s27, s95, s5
	s_add_u32 s34, s42, 0x34000
	s_addc_u32 s35, s43, 0
	s_add_u32 s36, s42, 0x33000
	v_readlane_b32 s40, v254, 10
	v_readlane_b32 s64, v254, 26
	v_readlane_b32 s4, v252, 14
	v_readlane_b32 s30, v254, 28
	s_addc_u32 s37, s43, 0
	v_readlane_b32 s41, v254, 11
	v_readlane_b32 s65, v254, 27
	s_mov_b32 s66, s4
	v_readlane_b32 s18, v253, 22
	s_mov_b32 s19, 0x1000000
	v_readlane_b32 s31, v254, 29
	.p2align	6

; __global__ void __launch_bounds__(512, 2) fwd_megakernel(Args a) {
;     ...
;         for (int row = gw * (ML / NGW), rend = row + ML / NGW; row < rend; row += 4) {
;             const int mr = row >> 13; const float* md = modl + (size_t)mr * 6144;
;             const float* xin = l == 0 ? a.in[0] + (size_t)row * DM : a.out + (size_t)row * DM;
;             if (!last) { const float* mdn = MOD + (size_t)(9 + mr) * 6144;
;                 row_op<4>(xin, YB + (size_t)row * DM, md + 2048, a.in[14] + l * 1024, a.out + (size_t)row * DM, HX + (size_t)row * DM, a.in[6] + 1024, mdn + 1024, mdn, lane,
;                           HX + (size_t)row * DM, md + 5120, a.in[18] + l * 1024);
;             } else row_op<4>(xin, YB + (size_t)row * DM, md + 2048, a.in[14] + l * 1024, a.out + (size_t)row * DM, nullptr, nullptr, nullptr, nullptr, lane,
;                              HX + (size_t)row * DM, md + 5120, a.in[18] + l * 1024);
;         }
.LBB0_871:
	s_or_b64 exec, exec, s[0:1]
	s_and_b64 vcc, exec, s[10:11]
	s_waitcnt lgkmcnt(0)
	s_barrier
	s_cbranch_vccnz .LBB0_881
	v_readlane_b32 s12, v255, 1
	v_readlane_b32 s4, v252, 0
	v_readlane_b32 s13, v255, 2
	s_add_u32 s0, s92, s12
	v_readlane_b32 s5, v252, 1
	v_readlane_b32 s6, v252, 2
	v_readlane_b32 s7, v252, 3
	v_readlane_b32 s8, v252, 4
	v_readlane_b32 s9, v252, 5
	s_addc_u32 s1, s93, s13
	v_readlane_b32 s10, v252, 6
	v_readlane_b32 s11, v252, 7
	s_mov_b64 s[4:5], s[8:9]
	s_mov_b64 s[6:7], s[10:11]
	s_add_u32 s10, s4, s12
	s_addc_u32 s11, s5, s13
	v_readlane_b32 s26, v254, 14
	v_readlane_b32 s4, v254, 22
	s_mov_b64 s[12:13], s[6:7]
	v_readlane_b32 s27, v254, 15
	s_mov_b32 s18, s4
	v_readlane_b32 s5, v254, 23
	s_branch .LBB0_874
	.p2align	6

; __global__ void __launch_bounds__(512, 2) fwd_megakernel(Args a) {
;     ...
;         if (!last) for (int row = ML + gw; row < MT; row += NGW) {
;             const float* md = modl + (size_t)8 * 6144; const float* mdn = MOD + (size_t)(9 + 8) * 6144;
;             row_op<1, 4>(X1C + (size_t)row * DM, (const bf16*)((const float*)(ws + WS_PART) + (size_t)(row - ML) * DM), md + 5120, a.in[18] + l * 1024, nullptr, HX + (size_t)row * DM, a.in[6] + 1024, mdn + 1024, mdn, lane);
;         }
.LBB0_882:
	v_readlane_b32 s0, v254, 63
	v_readlane_b32 s1, v255, 0
	v_readlane_b32 s18, v253, 36
	v_readlane_b32 s30, v254, 28
	s_and_b64 vcc, exec, s[0:1]
	v_readlane_b32 s16, v253, 22
	v_readlane_b32 s19, v253, 37
	s_mov_b32 s17, 0x1000000
	v_readlane_b32 s31, v254, 29
	s_cbranch_vccnz .LBB0_885
	v_readlane_b32 s4, v252, 0
	v_readlane_b32 s5, v252, 1
	v_readlane_b32 s6, v252, 2
	v_readlane_b32 s7, v252, 3
	v_readlane_b32 s8, v252, 4
	v_readlane_b32 s9, v252, 5
	v_readlane_b32 s10, v252, 6
	v_readlane_b32 s11, v252, 7
	s_mov_b64 s[4:5], s[8:9]
	s_add_u32 s0, s42, 0x35000
	s_mov_b64 s[6:7], s[10:11]
	s_addc_u32 s1, s43, 0
	v_readlane_b32 s6, v255, 1
	v_readlane_b32 s7, v255, 2
	s_add_u32 s4, s4, s6
	s_addc_u32 s5, s5, s7
	v_readlane_b32 s6, v254, 10
	v_readlane_b32 s8, v254, 26
	v_readlane_b32 s7, v254, 11
	v_readlane_b32 s9, v254, 27
	v_readlane_b32 s10, v252, 14
	.p2align	6
